# scan: L2-prefetch helpers fetch only the row-strided operands (K,Q rows / HQ rows), not the contiguous tiles
# speedup vs baseline: 1.0074x; 1.0059x over previous
.LBB0_319:
	v_mov_b64_e32 v[10:11], v[6:7]
	s_lshl_b64 s[18:19], s[2:3], 14
	v_readlane_b32 s36, v253, 23
	v_lshl_add_u64 v[16:17], v[2:3], 1, s[10:11]
	v_mov_b64_e32 v[8:9], v[4:5]
	v_readlane_b32 s37, v253, 24
	s_add_u32 s34, s36, s18
	global_load_dwordx4 v[8:11], v[16:17], off
	v_lshl_add_u64 v[16:17], v[16:17], 0, s[12:13]
	s_addc_u32 s35, s37, s19
	v_mov_b32_e32 v13, v3
	global_load_dwordx4 v[8:11], v[16:17], off
	v_lshl_add_u64 v[16:17], s[34:35], 0, v[12:13]
	v_readlane_b32 s34, v253, 21
	v_readlane_b32 s35, v253, 22
	s_add_u32 s18, s34, s18
	s_nop 0
	v_lshl_add_u64 v[16:17], v[16:17], 0, s[14:15]
	s_addc_u32 s19, s35, s19
	s_nop 0
	v_lshl_add_u64 v[16:17], s[18:19], 0, v[12:13]
	s_lshl_b64 s[18:19], s[16:17], 13
	s_nop 0
	s_add_u32 s18, s8, s18
	v_lshl_add_u64 v[16:17], v[16:17], 0, s[14:15]
	s_nop 0
	s_addc_u32 s19, s9, s19
	v_readlane_b32 s38, v253, 25
	v_readlane_b32 s39, v253, 26
	v_lshl_add_u64 v[16:17], s[18:19], 0, v[12:13]
	s_nop 0
	s_cbranch_execnz .LBB0_318
.LBB0_320:
	v_lshlrev_b64 v[8:9], 1, v[2:3]
	s_lshl_b64 s[18:19], s[2:3], 14
	v_readlane_b32 s36, v253, 29
	v_lshl_add_u64 v[10:11], s[60:61], 0, v[8:9]
	global_load_dwordx4 v[4:7], v[10:11], off
	v_readlane_b32 s37, v253, 30
	v_readlane_b32 s38, v253, 31
	v_readlane_b32 s39, v253, 32
	s_add_u32 s34, s36, s18
	v_lshl_add_u64 v[10:11], v[10:11], 0, s[12:13]
	global_load_dwordx4 v[4:7], v[10:11], off
	v_lshl_add_u64 v[8:9], s[70:71], 0, v[8:9]
	s_addc_u32 s35, s37, s19
	v_readlane_b32 s36, v253, 41
	global_load_dwordx4 v[4:7], v[8:9], off
	v_lshl_add_u64 v[8:9], v[8:9], 0, s[12:13]
	v_mov_b32_e32 v13, v3
	v_readlane_b32 s48, v253, 53
	global_load_dwordx4 v[4:7], v[8:9], off
	v_lshl_add_u64 v[8:9], s[34:35], 0, v[12:13]
	v_readlane_b32 s49, v253, 54
	s_add_u32 s18, s48, s18
	s_nop 0
	v_lshl_add_u64 v[8:9], v[8:9], 0, s[14:15]
	s_addc_u32 s19, s49, s19
	s_lshl_b64 s[16:17], s[16:17], 13
	s_nop 0
	v_lshl_add_u64 v[8:9], s[18:19], 0, v[12:13]
	s_add_u32 s18, s0, s16
	s_addc_u32 s19, s1, s17
	s_nop 0
	v_lshl_add_u64 v[8:9], v[8:9], 0, s[14:15]
	s_add_u32 s16, s88, s16
	v_readlane_b32 s2, v253, 33
	s_nop 0
	v_lshl_add_u64 v[8:9], s[18:19], 0, v[12:13]
	s_addc_u32 s17, s2, s17
	s_nop 0
	v_lshl_add_u64 v[8:9], s[16:17], 0, v[12:13]
	s_nop 0
	v_readlane_b32 s37, v253, 42
	v_mov_b64_e32 v[10:11], v[6:7]
	v_mov_b64_e32 v[8:9], v[4:5]
	v_readlane_b32 s38, v253, 43
	v_readlane_b32 s39, v253, 44
	v_readlane_b32 s40, v253, 45
	v_readlane_b32 s41, v253, 46
	v_readlane_b32 s42, v253, 47
	v_readlane_b32 s43, v253, 48
	v_readlane_b32 s44, v253, 49
	v_readlane_b32 s45, v253, 50
	v_readlane_b32 s46, v253, 51
	v_readlane_b32 s47, v253, 52
	v_readlane_b32 s50, v253, 55
	v_readlane_b32 s51, v253, 56
	s_add_i32 s22, s22, 1
	s_cmp_eq_u32 s22, 64
	s_cbranch_scc1 .LBB0_322
